# WKV scan (blocked decay): per-step LDS wait no longer waits for the R vector that is only needed one step later
# baseline (speedup 1.0000x reference)
.LBB0_545:
	s_mul_i32 s4, s93, 0x6000
	s_lshl_b32 s5, s93, 14
	v_add_u32_e32 v2, s4, v194
	v_add_u32_e32 v3, s4, v195
	v_add_u32_e32 v0, s5, v196
	ds_read_b128 v[24:27], v2 offset:16384
	ds_read_b64 v[44:45], v3 offset:12288
	ds_read_b128 v[36:39], v2 offset:8192
	ds_read_b128 v[32:35], v2 offset:20480
	ds_read_b128 v[40:43], v2 offset:0
	ds_read_b128 v[144:147], v2 offset:16640
	ds_read_b64 v[164:165], v3 offset:12544
	ds_read_b128 v[156:159], v2 offset:8448
	ds_read_b128 v[152:155], v2 offset:20736
	s_waitcnt lgkmcnt(4)
	v_pk_mul_f32 v[46:47], v[16:17], v[24:25] op_sel_hi:[1,0]
	v_pk_fma_f32 v[46:47], v[18:19], v[24:25], v[46:47] op_sel:[0,1,0] op_sel_hi:[1,1,1]
	v_pk_fma_f32 v[46:47], v[20:21], v[26:27], v[46:47] op_sel_hi:[1,0,1]
	v_pk_fma_f32 v[46:47], v[22:23], v[26:27], v[46:47] op_sel:[0,1,0] op_sel_hi:[1,1,1]
	ds_read_b128 v[160:163], v2 offset:256
	v_pk_fma_f32 v[16:17], v[44:45], v[36:37], v[16:17] op_sel_hi:[1,0,1]
	v_add_f32_dpp v48, v47, v46 quad_perm:[1,0,3,2] row_mask:0xf bank_mask:0xf bound_ctrl:1
	v_pk_fma_f32 v[18:19], v[44:45], v[36:37], v[18:19] op_sel:[0,1,0] op_sel_hi:[1,1,1]
	s_nop 0
	v_add_f32_dpp v48, v48, v48 quad_perm:[2,3,0,1] row_mask:0xf bank_mask:0xf bound_ctrl:1
	v_pk_fma_f32 v[20:21], v[44:45], v[38:39], v[20:21] op_sel_hi:[1,0,1]
	s_nop 0
	v_add_f32_dpp v48, v48, v48 row_ror:4 row_mask:0xf bank_mask:0xf bound_ctrl:1
	v_pk_fma_f32 v[22:23], v[44:45], v[38:39], v[22:23] op_sel:[0,1,0] op_sel_hi:[1,1,1]
	s_nop 0
	v_add_f32_dpp v48, v48, v48 row_ror:8 row_mask:0xf bank_mask:0xf bound_ctrl:1
	s_nop 1
	v_mov_b32_dpp v49, v48 quad_perm:[1,0,3,2] row_mask:0xf bank_mask:0xf bound_ctrl:1
	v_pk_fma_f32 v[16:17], v[48:49], v[32:33], v[16:17] op_sel_hi:[1,0,1] neg_lo:[0,1,0] neg_hi:[0,1,0]
	v_pk_fma_f32 v[18:19], v[48:49], v[32:33], v[18:19] op_sel:[0,1,0] op_sel_hi:[1,1,1] neg_lo:[0,1,0] neg_hi:[0,1,0]
	v_pk_fma_f32 v[20:21], v[48:49], v[34:35], v[20:21] op_sel_hi:[1,0,1] neg_lo:[0,1,0] neg_hi:[0,1,0]
	v_pk_fma_f32 v[22:23], v[48:49], v[34:35], v[22:23] op_sel:[0,1,0] op_sel_hi:[1,1,1] neg_lo:[0,1,0] neg_hi:[0,1,0]
	ds_read_b128 v[24:27], v2 offset:16896
	ds_read_b64 v[44:45], v3 offset:12800
	ds_read_b128 v[36:39], v2 offset:8704
	ds_read_b128 v[32:35], v2 offset:20992
	s_waitcnt lgkmcnt(5)
	v_pk_mul_f32 v[46:47], v[16:17], v[144:145] op_sel_hi:[1,0]
	v_pk_mul_f32 v[50:51], v[16:17], v[40:41] op_sel_hi:[1,0]
	v_pk_fma_f32 v[46:47], v[18:19], v[144:145], v[46:47] op_sel:[0,1,0] op_sel_hi:[1,1,1]
	v_pk_fma_f32 v[50:51], v[18:19], v[40:41], v[50:51] op_sel:[0,1,0] op_sel_hi:[1,1,1]
	v_pk_fma_f32 v[46:47], v[20:21], v[146:147], v[46:47] op_sel_hi:[1,0,1]
	v_pk_fma_f32 v[50:51], v[20:21], v[42:43], v[50:51] op_sel_hi:[1,0,1]
	v_pk_fma_f32 v[46:47], v[22:23], v[146:147], v[46:47] op_sel:[0,1,0] op_sel_hi:[1,1,1]
	v_pk_fma_f32 v[50:51], v[22:23], v[42:43], v[50:51] op_sel:[0,1,0] op_sel_hi:[1,1,1]
	ds_read_b128 v[40:43], v2 offset:512
	v_pk_fma_f32 v[16:17], v[164:165], v[156:157], v[16:17] op_sel_hi:[1,0,1]
	v_add_f32_dpp v48, v47, v46 quad_perm:[1,0,3,2] row_mask:0xf bank_mask:0xf bound_ctrl:1
	v_add_f32_dpp v52, v51, v50 quad_perm:[1,0,3,2] row_mask:0xf bank_mask:0xf bound_ctrl:1
	v_pk_fma_f32 v[18:19], v[164:165], v[156:157], v[18:19] op_sel:[0,1,0] op_sel_hi:[1,1,1]
	v_add_f32_dpp v48, v48, v48 quad_perm:[2,3,0,1] row_mask:0xf bank_mask:0xf bound_ctrl:1
	v_pk_fma_f32 v[20:21], v[164:165], v[158:159], v[20:21] op_sel_hi:[1,0,1]
	s_nop 0
	v_add_f32_dpp v48, v48, v48 row_ror:4 row_mask:0xf bank_mask:0xf bound_ctrl:1
	v_pk_fma_f32 v[22:23], v[164:165], v[158:159], v[22:23] op_sel:[0,1,0] op_sel_hi:[1,1,1]
	s_nop 0
	v_add_f32_dpp v48, v48, v48 row_ror:8 row_mask:0xf bank_mask:0xf bound_ctrl:1
	s_nop 1
	v_mov_b32_dpp v49, v48 quad_perm:[1,0,3,2] row_mask:0xf bank_mask:0xf bound_ctrl:1
	v_pk_fma_f32 v[16:17], v[48:49], v[152:153], v[16:17] op_sel_hi:[1,0,1] neg_lo:[0,1,0] neg_hi:[0,1,0]
	v_pk_fma_f32 v[18:19], v[48:49], v[152:153], v[18:19] op_sel:[0,1,0] op_sel_hi:[1,1,1] neg_lo:[0,1,0] neg_hi:[0,1,0]
	v_pk_fma_f32 v[20:21], v[48:49], v[154:155], v[20:21] op_sel_hi:[1,0,1] neg_lo:[0,1,0] neg_hi:[0,1,0]
	v_pk_fma_f32 v[22:23], v[48:49], v[154:155], v[22:23] op_sel:[0,1,0] op_sel_hi:[1,1,1] neg_lo:[0,1,0] neg_hi:[0,1,0]
	ds_read_b128 v[144:147], v2 offset:17152
	ds_read_b64 v[164:165], v3 offset:13056
	ds_read_b128 v[156:159], v2 offset:8960
	ds_read_b128 v[148:151], v2 offset:4864
	ds_read_b128 v[152:155], v2 offset:21248
	s_waitcnt lgkmcnt(6)
	v_pk_mul_f32 v[46:47], v[16:17], v[24:25] op_sel_hi:[1,0]
	v_pk_mul_f32 v[50:51], v[16:17], v[160:161] op_sel_hi:[1,0]
	v_pk_fma_f32 v[46:47], v[18:19], v[24:25], v[46:47] op_sel:[0,1,0] op_sel_hi:[1,1,1]
	v_pk_fma_f32 v[50:51], v[18:19], v[160:161], v[50:51] op_sel:[0,1,0] op_sel_hi:[1,1,1]
	v_pk_fma_f32 v[46:47], v[20:21], v[26:27], v[46:47] op_sel_hi:[1,0,1]
	v_pk_fma_f32 v[50:51], v[20:21], v[162:163], v[50:51] op_sel_hi:[1,0,1]
	v_pk_fma_f32 v[46:47], v[22:23], v[26:27], v[46:47] op_sel:[0,1,0] op_sel_hi:[1,1,1]
	v_pk_fma_f32 v[50:51], v[22:23], v[162:163], v[50:51] op_sel:[0,1,0] op_sel_hi:[1,1,1]
	ds_read_b128 v[160:163], v2 offset:768
	v_pk_fma_f32 v[16:17], v[44:45], v[36:37], v[16:17] op_sel_hi:[1,0,1]
	v_add_f32_dpp v48, v47, v46 quad_perm:[1,0,3,2] row_mask:0xf bank_mask:0xf bound_ctrl:1
	v_add_f32_dpp v53, v51, v50 quad_perm:[1,0,3,2] row_mask:0xf bank_mask:0xf bound_ctrl:1
	v_pk_fma_f32 v[18:19], v[44:45], v[36:37], v[18:19] op_sel:[0,1,0] op_sel_hi:[1,1,1]
	v_add_f32_dpp v48, v48, v48 quad_perm:[2,3,0,1] row_mask:0xf bank_mask:0xf bound_ctrl:1
	ds_write2st64_b32 v0, v52, v53 offset0:192 offset1:196
	v_pk_fma_f32 v[20:21], v[44:45], v[38:39], v[20:21] op_sel_hi:[1,0,1]
	v_add_f32_dpp v48, v48, v48 row_ror:4 row_mask:0xf bank_mask:0xf bound_ctrl:1
	v_pk_fma_f32 v[22:23], v[44:45], v[38:39], v[22:23] op_sel:[0,1,0] op_sel_hi:[1,1,1]
	s_nop 0
	v_add_f32_dpp v48, v48, v48 row_ror:8 row_mask:0xf bank_mask:0xf bound_ctrl:1
	s_nop 1
	v_mov_b32_dpp v49, v48 quad_perm:[1,0,3,2] row_mask:0xf bank_mask:0xf bound_ctrl:1
	v_pk_fma_f32 v[16:17], v[48:49], v[32:33], v[16:17] op_sel_hi:[1,0,1] neg_lo:[0,1,0] neg_hi:[0,1,0]
	v_pk_fma_f32 v[18:19], v[48:49], v[32:33], v[18:19] op_sel:[0,1,0] op_sel_hi:[1,1,1] neg_lo:[0,1,0] neg_hi:[0,1,0]
	v_pk_fma_f32 v[20:21], v[48:49], v[34:35], v[20:21] op_sel_hi:[1,0,1] neg_lo:[0,1,0] neg_hi:[0,1,0]
	v_pk_fma_f32 v[22:23], v[48:49], v[34:35], v[22:23] op_sel:[0,1,0] op_sel_hi:[1,1,1] neg_lo:[0,1,0] neg_hi:[0,1,0]
	ds_read_b128 v[24:27], v2 offset:17408
	ds_read_b64 v[44:45], v3 offset:13312
	ds_read_b128 v[36:39], v2 offset:9216
	ds_read_b128 v[32:35], v2 offset:21504
	s_waitcnt lgkmcnt(6)
	v_pk_mul_f32 v[46:47], v[16:17], v[144:145] op_sel_hi:[1,0]
	v_pk_mul_f32 v[50:51], v[16:17], v[40:41] op_sel_hi:[1,0]
	v_pk_fma_f32 v[46:47], v[18:19], v[144:145], v[46:47] op_sel:[0,1,0] op_sel_hi:[1,1,1]
	v_pk_fma_f32 v[50:51], v[18:19], v[40:41], v[50:51] op_sel:[0,1,0] op_sel_hi:[1,1,1]
	v_pk_fma_f32 v[46:47], v[20:21], v[146:147], v[46:47] op_sel_hi:[1,0,1]
	v_pk_fma_f32 v[50:51], v[20:21], v[42:43], v[50:51] op_sel_hi:[1,0,1]
	v_pk_fma_f32 v[46:47], v[22:23], v[146:147], v[46:47] op_sel:[0,1,0] op_sel_hi:[1,1,1]
	v_pk_fma_f32 v[50:51], v[22:23], v[42:43], v[50:51] op_sel:[0,1,0] op_sel_hi:[1,1,1]
	ds_read_b128 v[40:43], v2 offset:1024
	v_pk_fma_f32 v[16:17], v[164:165], v[156:157], v[16:17] op_sel_hi:[1,0,1]
	v_add_f32_dpp v48, v47, v46 quad_perm:[1,0,3,2] row_mask:0xf bank_mask:0xf bound_ctrl:1
	v_add_f32_dpp v52, v51, v50 quad_perm:[1,0,3,2] row_mask:0xf bank_mask:0xf bound_ctrl:1
	v_pk_fma_f32 v[18:19], v[164:165], v[156:157], v[18:19] op_sel:[0,1,0] op_sel_hi:[1,1,1]
	v_add_f32_dpp v48, v48, v48 quad_perm:[2,3,0,1] row_mask:0xf bank_mask:0xf bound_ctrl:1
	v_pk_fma_f32 v[20:21], v[164:165], v[158:159], v[20:21] op_sel_hi:[1,0,1]
	s_nop 0
	v_add_f32_dpp v48, v48, v48 row_ror:4 row_mask:0xf bank_mask:0xf bound_ctrl:1
	v_pk_fma_f32 v[22:23], v[164:165], v[158:159], v[22:23] op_sel:[0,1,0] op_sel_hi:[1,1,1]
	s_nop 0
	v_add_f32_dpp v48, v48, v48 row_ror:8 row_mask:0xf bank_mask:0xf bound_ctrl:1
	s_nop 1
	v_mov_b32_dpp v49, v48 quad_perm:[1,0,3,2] row_mask:0xf bank_mask:0xf bound_ctrl:1
	v_pk_fma_f32 v[16:17], v[48:49], v[152:153], v[16:17] op_sel_hi:[1,0,1] neg_lo:[0,1,0] neg_hi:[0,1,0]
	v_pk_fma_f32 v[18:19], v[48:49], v[152:153], v[18:19] op_sel:[0,1,0] op_sel_hi:[1,1,1] neg_lo:[0,1,0] neg_hi:[0,1,0]
	v_pk_fma_f32 v[20:21], v[48:49], v[154:155], v[20:21] op_sel_hi:[1,0,1] neg_lo:[0,1,0] neg_hi:[0,1,0]
	v_pk_fma_f32 v[22:23], v[48:49], v[154:155], v[22:23] op_sel:[0,1,0] op_sel_hi:[1,1,1] neg_lo:[0,1,0] neg_hi:[0,1,0]
	v_pk_mul_f32 v[16:17], v[16:17], v[148:149] op_sel_hi:[1,0]
	v_pk_mul_f32 v[18:19], v[18:19], v[148:149] op_sel:[0,1] op_sel_hi:[1,1]
	v_pk_mul_f32 v[20:21], v[20:21], v[150:151] op_sel_hi:[1,0]
	v_pk_mul_f32 v[22:23], v[22:23], v[150:151] op_sel:[0,1] op_sel_hi:[1,1]
	ds_read_b128 v[144:147], v2 offset:17664
	ds_read_b64 v[164:165], v3 offset:13568
	ds_read_b128 v[156:159], v2 offset:9472
	ds_read_b128 v[152:155], v2 offset:21760
	s_waitcnt lgkmcnt(5)
	v_pk_mul_f32 v[46:47], v[16:17], v[24:25] op_sel_hi:[1,0]
	v_pk_mul_f32 v[50:51], v[16:17], v[160:161] op_sel_hi:[1,0]
	v_pk_fma_f32 v[46:47], v[18:19], v[24:25], v[46:47] op_sel:[0,1,0] op_sel_hi:[1,1,1]
	v_pk_fma_f32 v[50:51], v[18:19], v[160:161], v[50:51] op_sel:[0,1,0] op_sel_hi:[1,1,1]
	v_pk_fma_f32 v[46:47], v[20:21], v[26:27], v[46:47] op_sel_hi:[1,0,1]
	v_pk_fma_f32 v[50:51], v[20:21], v[162:163], v[50:51] op_sel_hi:[1,0,1]
	v_pk_fma_f32 v[46:47], v[22:23], v[26:27], v[46:47] op_sel:[0,1,0] op_sel_hi:[1,1,1]
	v_pk_fma_f32 v[50:51], v[22:23], v[162:163], v[50:51] op_sel:[0,1,0] op_sel_hi:[1,1,1]
	ds_read_b128 v[160:163], v2 offset:1280
	v_pk_fma_f32 v[16:17], v[44:45], v[36:37], v[16:17] op_sel_hi:[1,0,1]
	v_add_f32_dpp v48, v47, v46 quad_perm:[1,0,3,2] row_mask:0xf bank_mask:0xf bound_ctrl:1
	v_add_f32_dpp v53, v51, v50 quad_perm:[1,0,3,2] row_mask:0xf bank_mask:0xf bound_ctrl:1
	v_pk_fma_f32 v[18:19], v[44:45], v[36:37], v[18:19] op_sel:[0,1,0] op_sel_hi:[1,1,1]
	v_add_f32_dpp v48, v48, v48 quad_perm:[2,3,0,1] row_mask:0xf bank_mask:0xf bound_ctrl:1
	ds_write2st64_b32 v0, v52, v53 offset0:200 offset1:204
	v_pk_fma_f32 v[20:21], v[44:45], v[38:39], v[20:21] op_sel_hi:[1,0,1]
	v_add_f32_dpp v48, v48, v48 row_ror:4 row_mask:0xf bank_mask:0xf bound_ctrl:1
	v_pk_fma_f32 v[22:23], v[44:45], v[38:39], v[22:23] op_sel:[0,1,0] op_sel_hi:[1,1,1]
	s_nop 0
	v_add_f32_dpp v48, v48, v48 row_ror:8 row_mask:0xf bank_mask:0xf bound_ctrl:1
	s_nop 1
	v_mov_b32_dpp v49, v48 quad_perm:[1,0,3,2] row_mask:0xf bank_mask:0xf bound_ctrl:1
	v_pk_fma_f32 v[16:17], v[48:49], v[32:33], v[16:17] op_sel_hi:[1,0,1] neg_lo:[0,1,0] neg_hi:[0,1,0]
	v_pk_fma_f32 v[18:19], v[48:49], v[32:33], v[18:19] op_sel:[0,1,0] op_sel_hi:[1,1,1] neg_lo:[0,1,0] neg_hi:[0,1,0]
	v_pk_fma_f32 v[20:21], v[48:49], v[34:35], v[20:21] op_sel_hi:[1,0,1] neg_lo:[0,1,0] neg_hi:[0,1,0]
	v_pk_fma_f32 v[22:23], v[48:49], v[34:35], v[22:23] op_sel:[0,1,0] op_sel_hi:[1,1,1] neg_lo:[0,1,0] neg_hi:[0,1,0]
	ds_read_b128 v[24:27], v2 offset:17920
	ds_read_b64 v[44:45], v3 offset:13824
	ds_read_b128 v[36:39], v2 offset:9728
	ds_read_b128 v[32:35], v2 offset:22016
	s_waitcnt lgkmcnt(6)
	v_pk_mul_f32 v[46:47], v[16:17], v[144:145] op_sel_hi:[1,0]
	v_pk_mul_f32 v[50:51], v[16:17], v[40:41] op_sel_hi:[1,0]
	v_pk_fma_f32 v[46:47], v[18:19], v[144:145], v[46:47] op_sel:[0,1,0] op_sel_hi:[1,1,1]
	v_pk_fma_f32 v[50:51], v[18:19], v[40:41], v[50:51] op_sel:[0,1,0] op_sel_hi:[1,1,1]
	v_pk_fma_f32 v[46:47], v[20:21], v[146:147], v[46:47] op_sel_hi:[1,0,1]
	v_pk_fma_f32 v[50:51], v[20:21], v[42:43], v[50:51] op_sel_hi:[1,0,1]
	v_pk_fma_f32 v[46:47], v[22:23], v[146:147], v[46:47] op_sel:[0,1,0] op_sel_hi:[1,1,1]
	v_pk_fma_f32 v[50:51], v[22:23], v[42:43], v[50:51] op_sel:[0,1,0] op_sel_hi:[1,1,1]
	ds_read_b128 v[40:43], v2 offset:1536
	v_pk_fma_f32 v[16:17], v[164:165], v[156:157], v[16:17] op_sel_hi:[1,0,1]
	v_add_f32_dpp v48, v47, v46 quad_perm:[1,0,3,2] row_mask:0xf bank_mask:0xf bound_ctrl:1
	v_add_f32_dpp v52, v51, v50 quad_perm:[1,0,3,2] row_mask:0xf bank_mask:0xf bound_ctrl:1
	v_pk_fma_f32 v[18:19], v[164:165], v[156:157], v[18:19] op_sel:[0,1,0] op_sel_hi:[1,1,1]
	v_add_f32_dpp v48, v48, v48 quad_perm:[2,3,0,1] row_mask:0xf bank_mask:0xf bound_ctrl:1
	v_pk_fma_f32 v[20:21], v[164:165], v[158:159], v[20:21] op_sel_hi:[1,0,1]
	s_nop 0
	v_add_f32_dpp v48, v48, v48 row_ror:4 row_mask:0xf bank_mask:0xf bound_ctrl:1
	v_pk_fma_f32 v[22:23], v[164:165], v[158:159], v[22:23] op_sel:[0,1,0] op_sel_hi:[1,1,1]
	s_nop 0
	v_add_f32_dpp v48, v48, v48 row_ror:8 row_mask:0xf bank_mask:0xf bound_ctrl:1
	s_nop 1
	v_mov_b32_dpp v49, v48 quad_perm:[1,0,3,2] row_mask:0xf bank_mask:0xf bound_ctrl:1
	v_pk_fma_f32 v[16:17], v[48:49], v[152:153], v[16:17] op_sel_hi:[1,0,1] neg_lo:[0,1,0] neg_hi:[0,1,0]
	v_pk_fma_f32 v[18:19], v[48:49], v[152:153], v[18:19] op_sel:[0,1,0] op_sel_hi:[1,1,1] neg_lo:[0,1,0] neg_hi:[0,1,0]
	v_pk_fma_f32 v[20:21], v[48:49], v[154:155], v[20:21] op_sel_hi:[1,0,1] neg_lo:[0,1,0] neg_hi:[0,1,0]
	v_pk_fma_f32 v[22:23], v[48:49], v[154:155], v[22:23] op_sel:[0,1,0] op_sel_hi:[1,1,1] neg_lo:[0,1,0] neg_hi:[0,1,0]
	ds_read_b128 v[144:147], v2 offset:18176
	ds_read_b64 v[164:165], v3 offset:14080
	ds_read_b128 v[156:159], v2 offset:9984
	ds_read_b128 v[148:151], v2 offset:5888
	ds_read_b128 v[152:155], v2 offset:22272
	s_waitcnt lgkmcnt(6)
	v_pk_mul_f32 v[46:47], v[16:17], v[24:25] op_sel_hi:[1,0]
	v_pk_mul_f32 v[50:51], v[16:17], v[160:161] op_sel_hi:[1,0]
	v_pk_fma_f32 v[46:47], v[18:19], v[24:25], v[46:47] op_sel:[0,1,0] op_sel_hi:[1,1,1]
	v_pk_fma_f32 v[50:51], v[18:19], v[160:161], v[50:51] op_sel:[0,1,0] op_sel_hi:[1,1,1]
	v_pk_fma_f32 v[46:47], v[20:21], v[26:27], v[46:47] op_sel_hi:[1,0,1]
	v_pk_fma_f32 v[50:51], v[20:21], v[162:163], v[50:51] op_sel_hi:[1,0,1]
	v_pk_fma_f32 v[46:47], v[22:23], v[26:27], v[46:47] op_sel:[0,1,0] op_sel_hi:[1,1,1]
	v_pk_fma_f32 v[50:51], v[22:23], v[162:163], v[50:51] op_sel:[0,1,0] op_sel_hi:[1,1,1]
	ds_read_b128 v[160:163], v2 offset:1792
	v_pk_fma_f32 v[16:17], v[44:45], v[36:37], v[16:17] op_sel_hi:[1,0,1]
	v_add_f32_dpp v48, v47, v46 quad_perm:[1,0,3,2] row_mask:0xf bank_mask:0xf bound_ctrl:1
	v_add_f32_dpp v53, v51, v50 quad_perm:[1,0,3,2] row_mask:0xf bank_mask:0xf bound_ctrl:1
	v_pk_fma_f32 v[18:19], v[44:45], v[36:37], v[18:19] op_sel:[0,1,0] op_sel_hi:[1,1,1]
	v_add_f32_dpp v48, v48, v48 quad_perm:[2,3,0,1] row_mask:0xf bank_mask:0xf bound_ctrl:1
	ds_write2st64_b32 v0, v52, v53 offset0:208 offset1:212
	v_pk_fma_f32 v[20:21], v[44:45], v[38:39], v[20:21] op_sel_hi:[1,0,1]
	v_add_f32_dpp v48, v48, v48 row_ror:4 row_mask:0xf bank_mask:0xf bound_ctrl:1
	v_pk_fma_f32 v[22:23], v[44:45], v[38:39], v[22:23] op_sel:[0,1,0] op_sel_hi:[1,1,1]
	s_nop 0
	v_add_f32_dpp v48, v48, v48 row_ror:8 row_mask:0xf bank_mask:0xf bound_ctrl:1
	s_nop 1
	v_mov_b32_dpp v49, v48 quad_perm:[1,0,3,2] row_mask:0xf bank_mask:0xf bound_ctrl:1
	v_pk_fma_f32 v[16:17], v[48:49], v[32:33], v[16:17] op_sel_hi:[1,0,1] neg_lo:[0,1,0] neg_hi:[0,1,0]
	v_pk_fma_f32 v[18:19], v[48:49], v[32:33], v[18:19] op_sel:[0,1,0] op_sel_hi:[1,1,1] neg_lo:[0,1,0] neg_hi:[0,1,0]
	v_pk_fma_f32 v[20:21], v[48:49], v[34:35], v[20:21] op_sel_hi:[1,0,1] neg_lo:[0,1,0] neg_hi:[0,1,0]
	v_pk_fma_f32 v[22:23], v[48:49], v[34:35], v[22:23] op_sel:[0,1,0] op_sel_hi:[1,1,1] neg_lo:[0,1,0] neg_hi:[0,1,0]
	ds_read_b128 v[24:27], v2 offset:18432
	ds_read_b64 v[44:45], v3 offset:14336
	ds_read_b128 v[36:39], v2 offset:10240
	ds_read_b128 v[32:35], v2 offset:22528
	s_waitcnt lgkmcnt(6)
	v_pk_mul_f32 v[46:47], v[16:17], v[144:145] op_sel_hi:[1,0]
	v_pk_mul_f32 v[50:51], v[16:17], v[40:41] op_sel_hi:[1,0]
	v_pk_fma_f32 v[46:47], v[18:19], v[144:145], v[46:47] op_sel:[0,1,0] op_sel_hi:[1,1,1]
	v_pk_fma_f32 v[50:51], v[18:19], v[40:41], v[50:51] op_sel:[0,1,0] op_sel_hi:[1,1,1]
	v_pk_fma_f32 v[46:47], v[20:21], v[146:147], v[46:47] op_sel_hi:[1,0,1]
	v_pk_fma_f32 v[50:51], v[20:21], v[42:43], v[50:51] op_sel_hi:[1,0,1]
	v_pk_fma_f32 v[46:47], v[22:23], v[146:147], v[46:47] op_sel:[0,1,0] op_sel_hi:[1,1,1]
	v_pk_fma_f32 v[50:51], v[22:23], v[42:43], v[50:51] op_sel:[0,1,0] op_sel_hi:[1,1,1]
	ds_read_b128 v[40:43], v2 offset:2048
	v_pk_fma_f32 v[16:17], v[164:165], v[156:157], v[16:17] op_sel_hi:[1,0,1]
	v_add_f32_dpp v48, v47, v46 quad_perm:[1,0,3,2] row_mask:0xf bank_mask:0xf bound_ctrl:1
	v_add_f32_dpp v52, v51, v50 quad_perm:[1,0,3,2] row_mask:0xf bank_mask:0xf bound_ctrl:1
	v_pk_fma_f32 v[18:19], v[164:165], v[156:157], v[18:19] op_sel:[0,1,0] op_sel_hi:[1,1,1]
	v_add_f32_dpp v48, v48, v48 quad_perm:[2,3,0,1] row_mask:0xf bank_mask:0xf bound_ctrl:1
	v_pk_fma_f32 v[20:21], v[164:165], v[158:159], v[20:21] op_sel_hi:[1,0,1]
	s_nop 0
	v_add_f32_dpp v48, v48, v48 row_ror:4 row_mask:0xf bank_mask:0xf bound_ctrl:1
	v_pk_fma_f32 v[22:23], v[164:165], v[158:159], v[22:23] op_sel:[0,1,0] op_sel_hi:[1,1,1]
	s_nop 0
	v_add_f32_dpp v48, v48, v48 row_ror:8 row_mask:0xf bank_mask:0xf bound_ctrl:1
	s_nop 1
	v_mov_b32_dpp v49, v48 quad_perm:[1,0,3,2] row_mask:0xf bank_mask:0xf bound_ctrl:1
	v_pk_fma_f32 v[16:17], v[48:49], v[152:153], v[16:17] op_sel_hi:[1,0,1] neg_lo:[0,1,0] neg_hi:[0,1,0]
	v_pk_fma_f32 v[18:19], v[48:49], v[152:153], v[18:19] op_sel:[0,1,0] op_sel_hi:[1,1,1] neg_lo:[0,1,0] neg_hi:[0,1,0]
	v_pk_fma_f32 v[20:21], v[48:49], v[154:155], v[20:21] op_sel_hi:[1,0,1] neg_lo:[0,1,0] neg_hi:[0,1,0]
	v_pk_fma_f32 v[22:23], v[48:49], v[154:155], v[22:23] op_sel:[0,1,0] op_sel_hi:[1,1,1] neg_lo:[0,1,0] neg_hi:[0,1,0]
	v_pk_mul_f32 v[16:17], v[16:17], v[148:149] op_sel_hi:[1,0]
	v_pk_mul_f32 v[18:19], v[18:19], v[148:149] op_sel:[0,1] op_sel_hi:[1,1]
	v_pk_mul_f32 v[20:21], v[20:21], v[150:151] op_sel_hi:[1,0]
	v_pk_mul_f32 v[22:23], v[22:23], v[150:151] op_sel:[0,1] op_sel_hi:[1,1]
	ds_read_b128 v[144:147], v2 offset:18688
	ds_read_b64 v[164:165], v3 offset:14592
	ds_read_b128 v[156:159], v2 offset:10496
	ds_read_b128 v[152:155], v2 offset:22784
	s_waitcnt lgkmcnt(5)
	v_pk_mul_f32 v[46:47], v[16:17], v[24:25] op_sel_hi:[1,0]
	v_pk_mul_f32 v[50:51], v[16:17], v[160:161] op_sel_hi:[1,0]
	v_pk_fma_f32 v[46:47], v[18:19], v[24:25], v[46:47] op_sel:[0,1,0] op_sel_hi:[1,1,1]
	v_pk_fma_f32 v[50:51], v[18:19], v[160:161], v[50:51] op_sel:[0,1,0] op_sel_hi:[1,1,1]
	v_pk_fma_f32 v[46:47], v[20:21], v[26:27], v[46:47] op_sel_hi:[1,0,1]
	v_pk_fma_f32 v[50:51], v[20:21], v[162:163], v[50:51] op_sel_hi:[1,0,1]
	v_pk_fma_f32 v[46:47], v[22:23], v[26:27], v[46:47] op_sel:[0,1,0] op_sel_hi:[1,1,1]
	v_pk_fma_f32 v[50:51], v[22:23], v[162:163], v[50:51] op_sel:[0,1,0] op_sel_hi:[1,1,1]
	ds_read_b128 v[160:163], v2 offset:2304
	v_pk_fma_f32 v[16:17], v[44:45], v[36:37], v[16:17] op_sel_hi:[1,0,1]
	v_add_f32_dpp v48, v47, v46 quad_perm:[1,0,3,2] row_mask:0xf bank_mask:0xf bound_ctrl:1
	v_add_f32_dpp v53, v51, v50 quad_perm:[1,0,3,2] row_mask:0xf bank_mask:0xf bound_ctrl:1
	v_pk_fma_f32 v[18:19], v[44:45], v[36:37], v[18:19] op_sel:[0,1,0] op_sel_hi:[1,1,1]
	v_add_f32_dpp v48, v48, v48 quad_perm:[2,3,0,1] row_mask:0xf bank_mask:0xf bound_ctrl:1
	ds_write2st64_b32 v0, v52, v53 offset0:216 offset1:220
	v_pk_fma_f32 v[20:21], v[44:45], v[38:39], v[20:21] op_sel_hi:[1,0,1]
	v_add_f32_dpp v48, v48, v48 row_ror:4 row_mask:0xf bank_mask:0xf bound_ctrl:1
	v_pk_fma_f32 v[22:23], v[44:45], v[38:39], v[22:23] op_sel:[0,1,0] op_sel_hi:[1,1,1]
	s_nop 0
	v_add_f32_dpp v48, v48, v48 row_ror:8 row_mask:0xf bank_mask:0xf bound_ctrl:1
	s_nop 1
	v_mov_b32_dpp v49, v48 quad_perm:[1,0,3,2] row_mask:0xf bank_mask:0xf bound_ctrl:1
	v_pk_fma_f32 v[16:17], v[48:49], v[32:33], v[16:17] op_sel_hi:[1,0,1] neg_lo:[0,1,0] neg_hi:[0,1,0]
	v_pk_fma_f32 v[18:19], v[48:49], v[32:33], v[18:19] op_sel:[0,1,0] op_sel_hi:[1,1,1] neg_lo:[0,1,0] neg_hi:[0,1,0]
	v_pk_fma_f32 v[20:21], v[48:49], v[34:35], v[20:21] op_sel_hi:[1,0,1] neg_lo:[0,1,0] neg_hi:[0,1,0]
	v_pk_fma_f32 v[22:23], v[48:49], v[34:35], v[22:23] op_sel:[0,1,0] op_sel_hi:[1,1,1] neg_lo:[0,1,0] neg_hi:[0,1,0]
	ds_read_b128 v[24:27], v2 offset:18944
	ds_read_b64 v[44:45], v3 offset:14848
	ds_read_b128 v[36:39], v2 offset:10752
	ds_read_b128 v[32:35], v2 offset:23040
	s_waitcnt lgkmcnt(6)
	v_pk_mul_f32 v[46:47], v[16:17], v[144:145] op_sel_hi:[1,0]
	v_pk_mul_f32 v[50:51], v[16:17], v[40:41] op_sel_hi:[1,0]
	v_pk_fma_f32 v[46:47], v[18:19], v[144:145], v[46:47] op_sel:[0,1,0] op_sel_hi:[1,1,1]
	v_pk_fma_f32 v[50:51], v[18:19], v[40:41], v[50:51] op_sel:[0,1,0] op_sel_hi:[1,1,1]
	v_pk_fma_f32 v[46:47], v[20:21], v[146:147], v[46:47] op_sel_hi:[1,0,1]
	v_pk_fma_f32 v[50:51], v[20:21], v[42:43], v[50:51] op_sel_hi:[1,0,1]
	v_pk_fma_f32 v[46:47], v[22:23], v[146:147], v[46:47] op_sel:[0,1,0] op_sel_hi:[1,1,1]
	v_pk_fma_f32 v[50:51], v[22:23], v[42:43], v[50:51] op_sel:[0,1,0] op_sel_hi:[1,1,1]
	ds_read_b128 v[40:43], v2 offset:2560
	v_pk_fma_f32 v[16:17], v[164:165], v[156:157], v[16:17] op_sel_hi:[1,0,1]
	v_add_f32_dpp v48, v47, v46 quad_perm:[1,0,3,2] row_mask:0xf bank_mask:0xf bound_ctrl:1
	v_add_f32_dpp v52, v51, v50 quad_perm:[1,0,3,2] row_mask:0xf bank_mask:0xf bound_ctrl:1
	v_pk_fma_f32 v[18:19], v[164:165], v[156:157], v[18:19] op_sel:[0,1,0] op_sel_hi:[1,1,1]
	v_add_f32_dpp v48, v48, v48 quad_perm:[2,3,0,1] row_mask:0xf bank_mask:0xf bound_ctrl:1
	v_pk_fma_f32 v[20:21], v[164:165], v[158:159], v[20:21] op_sel_hi:[1,0,1]
	s_nop 0
	v_add_f32_dpp v48, v48, v48 row_ror:4 row_mask:0xf bank_mask:0xf bound_ctrl:1
	v_pk_fma_f32 v[22:23], v[164:165], v[158:159], v[22:23] op_sel:[0,1,0] op_sel_hi:[1,1,1]
	s_nop 0
	v_add_f32_dpp v48, v48, v48 row_ror:8 row_mask:0xf bank_mask:0xf bound_ctrl:1
	s_nop 1
	v_mov_b32_dpp v49, v48 quad_perm:[1,0,3,2] row_mask:0xf bank_mask:0xf bound_ctrl:1
	v_pk_fma_f32 v[16:17], v[48:49], v[152:153], v[16:17] op_sel_hi:[1,0,1] neg_lo:[0,1,0] neg_hi:[0,1,0]
	v_pk_fma_f32 v[18:19], v[48:49], v[152:153], v[18:19] op_sel:[0,1,0] op_sel_hi:[1,1,1] neg_lo:[0,1,0] neg_hi:[0,1,0]
	v_pk_fma_f32 v[20:21], v[48:49], v[154:155], v[20:21] op_sel_hi:[1,0,1] neg_lo:[0,1,0] neg_hi:[0,1,0]
	v_pk_fma_f32 v[22:23], v[48:49], v[154:155], v[22:23] op_sel:[0,1,0] op_sel_hi:[1,1,1] neg_lo:[0,1,0] neg_hi:[0,1,0]
	ds_read_b128 v[144:147], v2 offset:19200
	ds_read_b64 v[164:165], v3 offset:15104
	ds_read_b128 v[156:159], v2 offset:11008
	ds_read_b128 v[148:151], v2 offset:6912
	ds_read_b128 v[152:155], v2 offset:23296
	s_waitcnt lgkmcnt(6)
	v_pk_mul_f32 v[46:47], v[16:17], v[24:25] op_sel_hi:[1,0]
	v_pk_mul_f32 v[50:51], v[16:17], v[160:161] op_sel_hi:[1,0]
	v_pk_fma_f32 v[46:47], v[18:19], v[24:25], v[46:47] op_sel:[0,1,0] op_sel_hi:[1,1,1]
	v_pk_fma_f32 v[50:51], v[18:19], v[160:161], v[50:51] op_sel:[0,1,0] op_sel_hi:[1,1,1]
	v_pk_fma_f32 v[46:47], v[20:21], v[26:27], v[46:47] op_sel_hi:[1,0,1]
	v_pk_fma_f32 v[50:51], v[20:21], v[162:163], v[50:51] op_sel_hi:[1,0,1]
	v_pk_fma_f32 v[46:47], v[22:23], v[26:27], v[46:47] op_sel:[0,1,0] op_sel_hi:[1,1,1]
	v_pk_fma_f32 v[50:51], v[22:23], v[162:163], v[50:51] op_sel:[0,1,0] op_sel_hi:[1,1,1]
	ds_read_b128 v[160:163], v2 offset:2816
	v_pk_fma_f32 v[16:17], v[44:45], v[36:37], v[16:17] op_sel_hi:[1,0,1]
	v_add_f32_dpp v48, v47, v46 quad_perm:[1,0,3,2] row_mask:0xf bank_mask:0xf bound_ctrl:1
	v_add_f32_dpp v53, v51, v50 quad_perm:[1,0,3,2] row_mask:0xf bank_mask:0xf bound_ctrl:1
	v_pk_fma_f32 v[18:19], v[44:45], v[36:37], v[18:19] op_sel:[0,1,0] op_sel_hi:[1,1,1]
	v_add_f32_dpp v48, v48, v48 quad_perm:[2,3,0,1] row_mask:0xf bank_mask:0xf bound_ctrl:1
	ds_write2st64_b32 v0, v52, v53 offset0:224 offset1:228
	v_pk_fma_f32 v[20:21], v[44:45], v[38:39], v[20:21] op_sel_hi:[1,0,1]
	v_add_f32_dpp v48, v48, v48 row_ror:4 row_mask:0xf bank_mask:0xf bound_ctrl:1
	v_pk_fma_f32 v[22:23], v[44:45], v[38:39], v[22:23] op_sel:[0,1,0] op_sel_hi:[1,1,1]
	s_nop 0
	v_add_f32_dpp v48, v48, v48 row_ror:8 row_mask:0xf bank_mask:0xf bound_ctrl:1
	s_nop 1
	v_mov_b32_dpp v49, v48 quad_perm:[1,0,3,2] row_mask:0xf bank_mask:0xf bound_ctrl:1
	v_pk_fma_f32 v[16:17], v[48:49], v[32:33], v[16:17] op_sel_hi:[1,0,1] neg_lo:[0,1,0] neg_hi:[0,1,0]
	v_pk_fma_f32 v[18:19], v[48:49], v[32:33], v[18:19] op_sel:[0,1,0] op_sel_hi:[1,1,1] neg_lo:[0,1,0] neg_hi:[0,1,0]
	v_pk_fma_f32 v[20:21], v[48:49], v[34:35], v[20:21] op_sel_hi:[1,0,1] neg_lo:[0,1,0] neg_hi:[0,1,0]
	v_pk_fma_f32 v[22:23], v[48:49], v[34:35], v[22:23] op_sel:[0,1,0] op_sel_hi:[1,1,1] neg_lo:[0,1,0] neg_hi:[0,1,0]
	ds_read_b128 v[24:27], v2 offset:19456
	ds_read_b64 v[44:45], v3 offset:15360
	ds_read_b128 v[36:39], v2 offset:11264
	ds_read_b128 v[32:35], v2 offset:23552
	s_waitcnt lgkmcnt(6)
	v_pk_mul_f32 v[46:47], v[16:17], v[144:145] op_sel_hi:[1,0]
	v_pk_mul_f32 v[50:51], v[16:17], v[40:41] op_sel_hi:[1,0]
	v_pk_fma_f32 v[46:47], v[18:19], v[144:145], v[46:47] op_sel:[0,1,0] op_sel_hi:[1,1,1]
	v_pk_fma_f32 v[50:51], v[18:19], v[40:41], v[50:51] op_sel:[0,1,0] op_sel_hi:[1,1,1]
	v_pk_fma_f32 v[46:47], v[20:21], v[146:147], v[46:47] op_sel_hi:[1,0,1]
	v_pk_fma_f32 v[50:51], v[20:21], v[42:43], v[50:51] op_sel_hi:[1,0,1]
	v_pk_fma_f32 v[46:47], v[22:23], v[146:147], v[46:47] op_sel:[0,1,0] op_sel_hi:[1,1,1]
	v_pk_fma_f32 v[50:51], v[22:23], v[42:43], v[50:51] op_sel:[0,1,0] op_sel_hi:[1,1,1]
	ds_read_b128 v[40:43], v2 offset:3072
	v_pk_fma_f32 v[16:17], v[164:165], v[156:157], v[16:17] op_sel_hi:[1,0,1]
	v_add_f32_dpp v48, v47, v46 quad_perm:[1,0,3,2] row_mask:0xf bank_mask:0xf bound_ctrl:1
	v_add_f32_dpp v52, v51, v50 quad_perm:[1,0,3,2] row_mask:0xf bank_mask:0xf bound_ctrl:1
	v_pk_fma_f32 v[18:19], v[164:165], v[156:157], v[18:19] op_sel:[0,1,0] op_sel_hi:[1,1,1]
	v_add_f32_dpp v48, v48, v48 quad_perm:[2,3,0,1] row_mask:0xf bank_mask:0xf bound_ctrl:1
	v_pk_fma_f32 v[20:21], v[164:165], v[158:159], v[20:21] op_sel_hi:[1,0,1]
	s_nop 0
	v_add_f32_dpp v48, v48, v48 row_ror:4 row_mask:0xf bank_mask:0xf bound_ctrl:1
	v_pk_fma_f32 v[22:23], v[164:165], v[158:159], v[22:23] op_sel:[0,1,0] op_sel_hi:[1,1,1]
	s_nop 0
	v_add_f32_dpp v48, v48, v48 row_ror:8 row_mask:0xf bank_mask:0xf bound_ctrl:1
	s_nop 1
	v_mov_b32_dpp v49, v48 quad_perm:[1,0,3,2] row_mask:0xf bank_mask:0xf bound_ctrl:1
	v_pk_fma_f32 v[16:17], v[48:49], v[152:153], v[16:17] op_sel_hi:[1,0,1] neg_lo:[0,1,0] neg_hi:[0,1,0]
	v_pk_fma_f32 v[18:19], v[48:49], v[152:153], v[18:19] op_sel:[0,1,0] op_sel_hi:[1,1,1] neg_lo:[0,1,0] neg_hi:[0,1,0]
	v_pk_fma_f32 v[20:21], v[48:49], v[154:155], v[20:21] op_sel_hi:[1,0,1] neg_lo:[0,1,0] neg_hi:[0,1,0]
	v_pk_fma_f32 v[22:23], v[48:49], v[154:155], v[22:23] op_sel:[0,1,0] op_sel_hi:[1,1,1] neg_lo:[0,1,0] neg_hi:[0,1,0]
	v_pk_mul_f32 v[16:17], v[16:17], v[148:149] op_sel_hi:[1,0]
	v_pk_mul_f32 v[18:19], v[18:19], v[148:149] op_sel:[0,1] op_sel_hi:[1,1]
	v_pk_mul_f32 v[20:21], v[20:21], v[150:151] op_sel_hi:[1,0]
	v_pk_mul_f32 v[22:23], v[22:23], v[150:151] op_sel:[0,1] op_sel_hi:[1,1]
	ds_read_b128 v[144:147], v2 offset:19712
	ds_read_b64 v[164:165], v3 offset:15616
	ds_read_b128 v[156:159], v2 offset:11520
	ds_read_b128 v[152:155], v2 offset:23808
	s_waitcnt lgkmcnt(5)
	v_pk_mul_f32 v[46:47], v[16:17], v[24:25] op_sel_hi:[1,0]
	v_pk_mul_f32 v[50:51], v[16:17], v[160:161] op_sel_hi:[1,0]
	v_pk_fma_f32 v[46:47], v[18:19], v[24:25], v[46:47] op_sel:[0,1,0] op_sel_hi:[1,1,1]
	v_pk_fma_f32 v[50:51], v[18:19], v[160:161], v[50:51] op_sel:[0,1,0] op_sel_hi:[1,1,1]
	v_pk_fma_f32 v[46:47], v[20:21], v[26:27], v[46:47] op_sel_hi:[1,0,1]
	v_pk_fma_f32 v[50:51], v[20:21], v[162:163], v[50:51] op_sel_hi:[1,0,1]
	v_pk_fma_f32 v[46:47], v[22:23], v[26:27], v[46:47] op_sel:[0,1,0] op_sel_hi:[1,1,1]
	v_pk_fma_f32 v[50:51], v[22:23], v[162:163], v[50:51] op_sel:[0,1,0] op_sel_hi:[1,1,1]
	ds_read_b128 v[160:163], v2 offset:3328
	v_pk_fma_f32 v[16:17], v[44:45], v[36:37], v[16:17] op_sel_hi:[1,0,1]
	v_add_f32_dpp v48, v47, v46 quad_perm:[1,0,3,2] row_mask:0xf bank_mask:0xf bound_ctrl:1
	v_add_f32_dpp v53, v51, v50 quad_perm:[1,0,3,2] row_mask:0xf bank_mask:0xf bound_ctrl:1
	v_pk_fma_f32 v[18:19], v[44:45], v[36:37], v[18:19] op_sel:[0,1,0] op_sel_hi:[1,1,1]
	v_add_f32_dpp v48, v48, v48 quad_perm:[2,3,0,1] row_mask:0xf bank_mask:0xf bound_ctrl:1
	ds_write2st64_b32 v0, v52, v53 offset0:232 offset1:236
	v_pk_fma_f32 v[20:21], v[44:45], v[38:39], v[20:21] op_sel_hi:[1,0,1]
	v_add_f32_dpp v48, v48, v48 row_ror:4 row_mask:0xf bank_mask:0xf bound_ctrl:1
	v_pk_fma_f32 v[22:23], v[44:45], v[38:39], v[22:23] op_sel:[0,1,0] op_sel_hi:[1,1,1]
	s_nop 0
	v_add_f32_dpp v48, v48, v48 row_ror:8 row_mask:0xf bank_mask:0xf bound_ctrl:1
	s_nop 1
	v_mov_b32_dpp v49, v48 quad_perm:[1,0,3,2] row_mask:0xf bank_mask:0xf bound_ctrl:1
	v_pk_fma_f32 v[16:17], v[48:49], v[32:33], v[16:17] op_sel_hi:[1,0,1] neg_lo:[0,1,0] neg_hi:[0,1,0]
	v_pk_fma_f32 v[18:19], v[48:49], v[32:33], v[18:19] op_sel:[0,1,0] op_sel_hi:[1,1,1] neg_lo:[0,1,0] neg_hi:[0,1,0]
	v_pk_fma_f32 v[20:21], v[48:49], v[34:35], v[20:21] op_sel_hi:[1,0,1] neg_lo:[0,1,0] neg_hi:[0,1,0]
	v_pk_fma_f32 v[22:23], v[48:49], v[34:35], v[22:23] op_sel:[0,1,0] op_sel_hi:[1,1,1] neg_lo:[0,1,0] neg_hi:[0,1,0]
	ds_read_b128 v[24:27], v2 offset:19968
	ds_read_b64 v[44:45], v3 offset:15872
	ds_read_b128 v[36:39], v2 offset:11776
	ds_read_b128 v[32:35], v2 offset:24064
	s_waitcnt lgkmcnt(6)
	v_pk_mul_f32 v[46:47], v[16:17], v[144:145] op_sel_hi:[1,0]
	v_pk_mul_f32 v[50:51], v[16:17], v[40:41] op_sel_hi:[1,0]
	v_pk_fma_f32 v[46:47], v[18:19], v[144:145], v[46:47] op_sel:[0,1,0] op_sel_hi:[1,1,1]
	v_pk_fma_f32 v[50:51], v[18:19], v[40:41], v[50:51] op_sel:[0,1,0] op_sel_hi:[1,1,1]
	v_pk_fma_f32 v[46:47], v[20:21], v[146:147], v[46:47] op_sel_hi:[1,0,1]
	v_pk_fma_f32 v[50:51], v[20:21], v[42:43], v[50:51] op_sel_hi:[1,0,1]
	v_pk_fma_f32 v[46:47], v[22:23], v[146:147], v[46:47] op_sel:[0,1,0] op_sel_hi:[1,1,1]
	v_pk_fma_f32 v[50:51], v[22:23], v[42:43], v[50:51] op_sel:[0,1,0] op_sel_hi:[1,1,1]
	ds_read_b128 v[40:43], v2 offset:3584
	v_pk_fma_f32 v[16:17], v[164:165], v[156:157], v[16:17] op_sel_hi:[1,0,1]
	v_add_f32_dpp v48, v47, v46 quad_perm:[1,0,3,2] row_mask:0xf bank_mask:0xf bound_ctrl:1
	v_add_f32_dpp v52, v51, v50 quad_perm:[1,0,3,2] row_mask:0xf bank_mask:0xf bound_ctrl:1
	v_pk_fma_f32 v[18:19], v[164:165], v[156:157], v[18:19] op_sel:[0,1,0] op_sel_hi:[1,1,1]
	v_add_f32_dpp v48, v48, v48 quad_perm:[2,3,0,1] row_mask:0xf bank_mask:0xf bound_ctrl:1
	v_pk_fma_f32 v[20:21], v[164:165], v[158:159], v[20:21] op_sel_hi:[1,0,1]
	s_nop 0
	v_add_f32_dpp v48, v48, v48 row_ror:4 row_mask:0xf bank_mask:0xf bound_ctrl:1
	v_pk_fma_f32 v[22:23], v[164:165], v[158:159], v[22:23] op_sel:[0,1,0] op_sel_hi:[1,1,1]
	s_nop 0
	v_add_f32_dpp v48, v48, v48 row_ror:8 row_mask:0xf bank_mask:0xf bound_ctrl:1
	s_nop 1
	v_mov_b32_dpp v49, v48 quad_perm:[1,0,3,2] row_mask:0xf bank_mask:0xf bound_ctrl:1
	v_pk_fma_f32 v[16:17], v[48:49], v[152:153], v[16:17] op_sel_hi:[1,0,1] neg_lo:[0,1,0] neg_hi:[0,1,0]
	v_pk_fma_f32 v[18:19], v[48:49], v[152:153], v[18:19] op_sel:[0,1,0] op_sel_hi:[1,1,1] neg_lo:[0,1,0] neg_hi:[0,1,0]
	v_pk_fma_f32 v[20:21], v[48:49], v[154:155], v[20:21] op_sel_hi:[1,0,1] neg_lo:[0,1,0] neg_hi:[0,1,0]
	v_pk_fma_f32 v[22:23], v[48:49], v[154:155], v[22:23] op_sel:[0,1,0] op_sel_hi:[1,1,1] neg_lo:[0,1,0] neg_hi:[0,1,0]
	ds_read_b128 v[144:147], v2 offset:20224
	ds_read_b64 v[164:165], v3 offset:16128
	ds_read_b128 v[156:159], v2 offset:12032
	ds_read_b128 v[148:151], v2 offset:7936
	ds_read_b128 v[152:155], v2 offset:24320
	s_waitcnt lgkmcnt(6)
	v_pk_mul_f32 v[46:47], v[16:17], v[24:25] op_sel_hi:[1,0]
	v_pk_mul_f32 v[50:51], v[16:17], v[160:161] op_sel_hi:[1,0]
	v_pk_fma_f32 v[46:47], v[18:19], v[24:25], v[46:47] op_sel:[0,1,0] op_sel_hi:[1,1,1]
	v_pk_fma_f32 v[50:51], v[18:19], v[160:161], v[50:51] op_sel:[0,1,0] op_sel_hi:[1,1,1]
	v_pk_fma_f32 v[46:47], v[20:21], v[26:27], v[46:47] op_sel_hi:[1,0,1]
	v_pk_fma_f32 v[50:51], v[20:21], v[162:163], v[50:51] op_sel_hi:[1,0,1]
	v_pk_fma_f32 v[46:47], v[22:23], v[26:27], v[46:47] op_sel:[0,1,0] op_sel_hi:[1,1,1]
	v_pk_fma_f32 v[50:51], v[22:23], v[162:163], v[50:51] op_sel:[0,1,0] op_sel_hi:[1,1,1]
	ds_read_b128 v[160:163], v2 offset:3840
	v_pk_fma_f32 v[16:17], v[44:45], v[36:37], v[16:17] op_sel_hi:[1,0,1]
	v_add_f32_dpp v48, v47, v46 quad_perm:[1,0,3,2] row_mask:0xf bank_mask:0xf bound_ctrl:1
	v_add_f32_dpp v53, v51, v50 quad_perm:[1,0,3,2] row_mask:0xf bank_mask:0xf bound_ctrl:1
	v_pk_fma_f32 v[18:19], v[44:45], v[36:37], v[18:19] op_sel:[0,1,0] op_sel_hi:[1,1,1]
	v_add_f32_dpp v48, v48, v48 quad_perm:[2,3,0,1] row_mask:0xf bank_mask:0xf bound_ctrl:1
	ds_write2st64_b32 v0, v52, v53 offset0:240 offset1:244
	v_pk_fma_f32 v[20:21], v[44:45], v[38:39], v[20:21] op_sel_hi:[1,0,1]
	v_add_f32_dpp v48, v48, v48 row_ror:4 row_mask:0xf bank_mask:0xf bound_ctrl:1
	v_pk_fma_f32 v[22:23], v[44:45], v[38:39], v[22:23] op_sel:[0,1,0] op_sel_hi:[1,1,1]
	s_nop 0
	v_add_f32_dpp v48, v48, v48 row_ror:8 row_mask:0xf bank_mask:0xf bound_ctrl:1
	s_nop 1
	v_mov_b32_dpp v49, v48 quad_perm:[1,0,3,2] row_mask:0xf bank_mask:0xf bound_ctrl:1
	v_pk_fma_f32 v[16:17], v[48:49], v[32:33], v[16:17] op_sel_hi:[1,0,1] neg_lo:[0,1,0] neg_hi:[0,1,0]
	v_pk_fma_f32 v[18:19], v[48:49], v[32:33], v[18:19] op_sel:[0,1,0] op_sel_hi:[1,1,1] neg_lo:[0,1,0] neg_hi:[0,1,0]
	v_pk_fma_f32 v[20:21], v[48:49], v[34:35], v[20:21] op_sel_hi:[1,0,1] neg_lo:[0,1,0] neg_hi:[0,1,0]
	v_pk_fma_f32 v[22:23], v[48:49], v[34:35], v[22:23] op_sel:[0,1,0] op_sel_hi:[1,1,1] neg_lo:[0,1,0] neg_hi:[0,1,0]
	s_waitcnt lgkmcnt(2)
	v_pk_mul_f32 v[46:47], v[16:17], v[144:145] op_sel_hi:[1,0]
	v_pk_mul_f32 v[50:51], v[16:17], v[40:41] op_sel_hi:[1,0]
	v_pk_fma_f32 v[46:47], v[18:19], v[144:145], v[46:47] op_sel:[0,1,0] op_sel_hi:[1,1,1]
	v_pk_fma_f32 v[50:51], v[18:19], v[40:41], v[50:51] op_sel:[0,1,0] op_sel_hi:[1,1,1]
	v_pk_fma_f32 v[46:47], v[20:21], v[146:147], v[46:47] op_sel_hi:[1,0,1]
	v_pk_fma_f32 v[50:51], v[20:21], v[42:43], v[50:51] op_sel_hi:[1,0,1]
	v_pk_fma_f32 v[46:47], v[22:23], v[146:147], v[46:47] op_sel:[0,1,0] op_sel_hi:[1,1,1]
	v_pk_fma_f32 v[50:51], v[22:23], v[42:43], v[50:51] op_sel:[0,1,0] op_sel_hi:[1,1,1]
	v_pk_fma_f32 v[16:17], v[164:165], v[156:157], v[16:17] op_sel_hi:[1,0,1]
	v_add_f32_dpp v48, v47, v46 quad_perm:[1,0,3,2] row_mask:0xf bank_mask:0xf bound_ctrl:1
	v_add_f32_dpp v52, v51, v50 quad_perm:[1,0,3,2] row_mask:0xf bank_mask:0xf bound_ctrl:1
	v_pk_fma_f32 v[18:19], v[164:165], v[156:157], v[18:19] op_sel:[0,1,0] op_sel_hi:[1,1,1]
	v_add_f32_dpp v48, v48, v48 quad_perm:[2,3,0,1] row_mask:0xf bank_mask:0xf bound_ctrl:1
	v_pk_fma_f32 v[20:21], v[164:165], v[158:159], v[20:21] op_sel_hi:[1,0,1]
	s_nop 0
	v_add_f32_dpp v48, v48, v48 row_ror:4 row_mask:0xf bank_mask:0xf bound_ctrl:1
	v_pk_fma_f32 v[22:23], v[164:165], v[158:159], v[22:23] op_sel:[0,1,0] op_sel_hi:[1,1,1]
	s_nop 0
	v_add_f32_dpp v48, v48, v48 row_ror:8 row_mask:0xf bank_mask:0xf bound_ctrl:1
	s_nop 1
	v_mov_b32_dpp v49, v48 quad_perm:[1,0,3,2] row_mask:0xf bank_mask:0xf bound_ctrl:1
	v_pk_fma_f32 v[16:17], v[48:49], v[152:153], v[16:17] op_sel_hi:[1,0,1] neg_lo:[0,1,0] neg_hi:[0,1,0]
	v_pk_fma_f32 v[18:19], v[48:49], v[152:153], v[18:19] op_sel:[0,1,0] op_sel_hi:[1,1,1] neg_lo:[0,1,0] neg_hi:[0,1,0]
	v_pk_fma_f32 v[20:21], v[48:49], v[154:155], v[20:21] op_sel_hi:[1,0,1] neg_lo:[0,1,0] neg_hi:[0,1,0]
	v_pk_fma_f32 v[22:23], v[48:49], v[154:155], v[22:23] op_sel:[0,1,0] op_sel_hi:[1,1,1] neg_lo:[0,1,0] neg_hi:[0,1,0]
	v_pk_mul_f32 v[16:17], v[16:17], v[148:149] op_sel_hi:[1,0]
	v_pk_mul_f32 v[18:19], v[18:19], v[148:149] op_sel:[0,1] op_sel_hi:[1,1]
	v_pk_mul_f32 v[20:21], v[20:21], v[150:151] op_sel_hi:[1,0]
	v_pk_mul_f32 v[22:23], v[22:23], v[150:151] op_sel:[0,1] op_sel_hi:[1,1]
	s_waitcnt lgkmcnt(1)
	v_pk_mul_f32 v[50:51], v[16:17], v[160:161] op_sel_hi:[1,0]
	v_pk_fma_f32 v[50:51], v[18:19], v[160:161], v[50:51] op_sel:[0,1,0] op_sel_hi:[1,1,1]
	v_pk_fma_f32 v[50:51], v[20:21], v[162:163], v[50:51] op_sel_hi:[1,0,1]
	v_pk_fma_f32 v[50:51], v[22:23], v[162:163], v[50:51] op_sel:[0,1,0] op_sel_hi:[1,1,1]
	s_nop 1
	v_add_f32_dpp v53, v51, v50 quad_perm:[1,0,3,2] row_mask:0xf bank_mask:0xf bound_ctrl:1
	ds_write2st64_b32 v0, v52, v53 offset0:248 offset1:252
